# MLA loop: every 8-byte instruction on an 8-byte boundary (VOP2 ops re-encoded as VOP3 / waits re-placed to make all 4-byte runs even)
# speedup vs baseline: 1.0041x; 1.0041x over previous
; #define LAS __attribute__((address_space(3)))
; #define GAS __attribute__((address_space(1)))
; __device__ __forceinline__ void attn_unit(const bf16_t* Qh, const bf16_t* Kh, const bf16_t* Vh, bf16_t* Oh  , int S, int qb, LAS unsigned char* lds, int tid) {
;     const int lane = tid & 63, r32 = lane & 31, hi = lane >> 5; const int wid = __builtin_amdgcn_readfirstlane(tid >> 6);
;     const int qrow = qb * 512 + wid * 64 + r32;
;     const bf16_t* Qw = Qh + (size_t)qrow * 96 + 8 * hi;
;     LAS unsigned char* ql = lds + QOFF + wid * 12288 + lane * 16;
; #pragma unroll
;     for (int s = 0; s < 6; ++s) { *(LAS bf16x8*)(ql + s * 1024) = GLD(bf16x8, Qw + 16 * s); *(LAS bf16x8*)(ql + (6 + s) * 1024) = GLD(bf16x8, Qw + 32 * 96 + 16 * s); }
;     const bool has1 = tid < 256; const int kc0 = tid, kc1 = has1 ? tid + 512 : tid;
;     const unsigned kd0 = (unsigned)((kc0 / 12) * KPITCH + (kc0 % 12) * 16);
;     const unsigned kd1 = has1 ? (unsigned)((kc1 / 12) * KPITCH + (kc1 % 12) * 16) : (unsigned)(DUMMY + (tid - 256) * 16);
;     const unsigned kd1n = has1 ? BUF : 0u;
;     const unsigned vd = (unsigned)(KBYTES + ((tid & 7) >> 2) * 4096 + (tid >> 3) * 64 + (tid & 3) * 16);
;     const GAS u32x4* Kg = (const GAS u32x4*)Kh; const GAS u32x4* Vg = (const GAS u32x4*)Vh;
;     const int NT = S >> 6;
;     u32x4 ka = GLD(u32x4, Kg + kc0), kb = GLD(u32x4, Kg + kc1), va = GLD(u32x4, Vg + tid);
;     *(LAS u32x4*)(lds + kd0) = ka; *(LAS u32x4*)(lds + kd1) = kb; *(LAS u32x4*)(lds + vd) = va;
;     __syncthreads();
;     f32x16 oa0 = {}, oa1 = {}, ob0 = {}, ob1 = {}; float ma = 0.f, la = 0.f, mb = 0.f, lb = 0.f;
.LBB0_76:
	s_abs_i32 s1, s24
	s_mul_hi_u32 s4, s1, s19
	s_mul_i32 s16, s4, s13
	s_sub_i32 s1, s1, s16
	s_ashr_i32 s0, s24, 31
	s_add_i32 s16, s4, 1
	s_sub_i32 s17, s1, s13
	s_cmp_ge_u32 s1, s13
	s_cselect_b32 s4, s16, s4
	s_cselect_b32 s1, s17, s1
	s_add_i32 s16, s4, 1
	s_cmp_ge_u32 s1, s13
	s_cselect_b32 s1, s16, s4
	s_xor_b32 s1, s1, s0
	s_sub_i32 s0, s1, s0
	s_mul_i32 s1, s0, s13
	s_sub_i32 s4, s24, s1
	s_ashr_i32 s1, s0, 31
	s_lshl_b64 s[26:27], s[0:1], s82
	s_mul_i32 s1, s27, 0xc0
	s_mul_hi_u32 s16, s26, 0xc0
	s_add_i32 s1, s16, s1
	s_mul_i32 s16, s26, 0xc0
	s_add_u32 s40, s96, s16
	s_addc_u32 s41, s97, s1
	s_add_u32 s16, s84, s16
	s_addc_u32 s17, s85, s1
	s_lshl_b64 s[26:27], s[26:27], 7
	s_add_u32 s26, s86, s26
	v_readfirstlane_b32 s1, v172
	s_addc_u32 s27, s87, s27
	s_lshl_b32 s4, s4, 9
	s_and_b32 s25, s1, 0xffffffc0
	s_add_i32 s4, s4, s25
	v_or_b32_e32 v136, s4, v148
	v_mov_b64_e32 v[0:1], s[40:41]
	v_mad_i64_i32 v[0:1], s[40:41], v136, s75, v[0:1]
	v_lshl_add_u64 v[40:41], v[0:1], 0, v[168:169]
	v_add_co_u32_e32 v44, vcc, s33, v40
	v_lshlrev_b64 v[60:61], 4, v[172:173]
	s_nop 0
	v_addc_co_u32_e32 v45, vcc, 0, v41, vcc
	v_lshl_add_u64 v[48:49], s[16:17], 0, v[60:61]
	global_load_dwordx4 v[0:3], v[40:41], off
	global_load_dwordx4 v[4:7], v[40:41], off offset:32
	global_load_dwordx4 v[8:11], v[40:41], off offset:64
	global_load_dwordx4 v[12:15], v[44:45], off offset:2080
	global_load_dwordx4 v[16:19], v[44:45], off offset:2112
	global_load_dwordx4 v[20:23], v[40:41], off offset:96
	global_load_dwordx4 v[24:27], v[40:41], off offset:128
	global_load_dwordx4 v[28:31], v[44:45], off offset:2144
	global_load_dwordx4 v[32:35], v[44:45], off offset:2176
	global_load_dwordx4 v[36:39], v[44:45], off offset:2048
	s_nop 0
	global_load_dwordx4 v[40:43], v[40:41], off offset:160
	s_nop 0
	global_load_dwordx4 v[44:47], v[44:45], off offset:2208
	s_nop 0
	global_load_dwordx4 v[48:51], v[48:49], off
	v_lshlrev_b64 v[62:63], 4, v[132:133]
	v_lshl_add_u64 v[52:53], s[16:17], 0, v[62:63]
	global_load_dwordx4 v[52:55], v[52:53], off
	v_lshl_add_u64 v[138:139], s[26:27], 0, v[60:61]
	global_load_dwordx4 v[56:59], v[138:139], off
	s_lshr_b32 s1, s1, 6
	s_mulk_i32 s1, 0x3000
	v_add_u32_e32 v135, s1, v149
	v_add_u32_e32 v163, 0, v150
	v_add_u32_e32 v162, 0, v157
	s_add_u32 s26, s16, 0x3000
	s_movk_i32 s1, 0x2000
	s_addc_u32 s27, s17, 0
	v_ashrrev_i32_e32 v137, 31, v136
	s_waitcnt vmcnt(0)
	ds_write_b128 v135, v[0:3] offset:43008
	s_waitcnt vmcnt(13)
	ds_write_b128 v135, v[4:7] offset:44032
	s_waitcnt vmcnt(12)
	ds_write_b128 v135, v[8:11] offset:45056
	s_waitcnt vmcnt(9)
	ds_write_b128 v135, v[20:23] offset:46080
	s_waitcnt vmcnt(8)
	ds_write_b128 v135, v[24:27] offset:47104
	s_waitcnt vmcnt(5)
	ds_write_b128 v135, v[36:39] offset:49152
	ds_write_b128 v135, v[12:15] offset:50176
	ds_write_b128 v135, v[16:19] offset:51200
	ds_write_b128 v135, v[28:31] offset:52224
	ds_write_b128 v135, v[32:35] offset:53248
	s_waitcnt vmcnt(4)
	ds_write_b128 v135, v[40:43] offset:48128
	s_waitcnt vmcnt(3)
	ds_write_b128 v135, v[44:47] offset:54272
	s_waitcnt vmcnt(2)
	ds_write_b128 v163, v[48:51]
	s_waitcnt vmcnt(1)
	ds_write_b128 v156, v[52:55]
	s_waitcnt vmcnt(0)
	ds_write_b128 v162, v[56:59] offset:13312
	s_waitcnt lgkmcnt(0)
	s_barrier
	s_cmp_eq_u32 s100, 0
	s_cbranch_scc1 .Lalt_entry
	v_mov_b64_e32 v[0:1], 0
	v_mov_b64_e32 v[2:3], 0
	v_mov_b64_e32 v[4:5], 0
	v_mov_b64_e32 v[6:7], 0
	v_mov_b64_e32 v[8:9], 0
	v_mov_b64_e32 v[10:11], 0
	v_mov_b64_e32 v[12:13], 0
	v_mov_b64_e32 v[14:15], 0
	v_mov_b64_e32 v[16:17], 0
	v_mov_b64_e32 v[18:19], 0
	v_mov_b64_e32 v[20:21], 0
	v_mov_b64_e32 v[22:23], 0
	v_mov_b64_e32 v[24:25], 0
	v_mov_b64_e32 v[26:27], 0
	v_mov_b64_e32 v[28:29], 0
	v_mov_b64_e32 v[30:31], 0
	v_mov_b64_e32 v[32:33], 0
	v_mov_b64_e32 v[34:35], 0
	v_mov_b64_e32 v[36:37], 0
	v_mov_b64_e32 v[38:39], 0
	v_mov_b64_e32 v[40:41], 0
	v_mov_b64_e32 v[42:43], 0
	v_mov_b64_e32 v[44:45], 0
	v_mov_b64_e32 v[46:47], 0
	v_mov_b64_e32 v[48:49], 0
	v_mov_b64_e32 v[50:51], 0
	v_mov_b64_e32 v[52:53], 0
	v_mov_b64_e32 v[54:55], 0
	v_mov_b64_e32 v[56:57], 0
	v_mov_b64_e32 v[58:59], 0
	v_mov_b64_e32 v[60:61], 0
	v_mov_b64_e32 v[62:63], 0
	v_mov_b32_e32 v140, 0
	v_mov_b32_e32 v141, 0
	v_lshlrev_b32_e32 v171, 4, v172
	v_lshlrev_b32_e32 v184, 4, v132
	v_lshlrev_b32_e32 v146, 4, v174
	v_readfirstlane_b32 s100, v138
	v_readfirstlane_b32 s101, v139
	s_add_u32 s26, s16, 0x3000
	s_addc_u32 s27, s17, 0
	s_mov_b32 s1, 1
	v_readfirstlane_b32 s4, v172
	s_nop 3
	s_cmp_ge_u32 s4, 0x100
	s_nop 0
	s_nop 0

; #define LAS __attribute__((address_space(3)))
; __device__ __forceinline__ float swap_max(float m) { auto rr = __builtin_amdgcn_permlane32_swap(__float_as_uint(m), __float_as_uint(m), false, false); return fmaxf(__uint_as_float(rr[0]), __uint_as_float(rr[1])); }
; __device__ __forceinline__ void softmax_blk(f32x16& p0, f32x16& p1, f32x16& o0, f32x16& o1, float& mhat, float& lrun, u32x4 (&pf)[4], bool first) {
;     float r0 = max2_(p0[0], p0[1]), r1 = max2_(p1[0], p1[1]);
; #pragma unroll
;     for (int e = 2; e < 16; ++e) { r0 = max2_(r0, p0[e]); r1 = max2_(r1, p1[e]); }
;     const float rm = swap_max(max2_(r0, r1));
;     if (first || __any(rm - mhat > THR)) {
;         const float mn = first ? rm : fmaxf(rm, mhat); const float f = first ? 0.f : __builtin_amdgcn_exp2f(mhat - mn); mhat = mn; lrun *= f;
; #pragma unroll
;         for (int e = 0; e < 16; ++e) { o0[e] *= f; o1[e] *= f; }
;     }
;     float s0 = 0.f, s1 = 0.f;
; #pragma unroll
;     for (int e = 0; e < 16; ++e) { p0[e] = __builtin_amdgcn_exp2f(p0[e] - mhat); p1[e] = __builtin_amdgcn_exp2f(p1[e] - mhat); s0 += p0[e]; s1 += p1[e]; }
;     lrun += s0 + s1;
;     pf[0] = MLA_PACK(p0, 0); pf[1] = MLA_PACK(p0, 8); pf[2] = MLA_PACK(p1, 0); pf[3] = MLA_PACK(p1, 8);
; }
; __device__ __forceinline__ void attn_unit(const bf16_t* Qh, const bf16_t* Kh, const bf16_t* Vh, bf16_t* Oh  , int S, int qb, LAS unsigned char* lds, int tid) {
;     ...
;             softmax_blk(p0, p1, oa0, oa1, ma, la, pf, t == 0);
;             pv_blk(pf, oa0, oa1, lds + cur + vb);
;         }
;         __builtin_amdgcn_sched_barrier(0);
;         {
;             f32x16 p0 = {}, p1 = {};
; #pragma unroll
;             for (int s = 0; s < 6; ++s) {
;                 const bf16x8 a0 = *(const LAS bf16x8*)(lds + cur + kfo + s * 32), a1 = *(const LAS bf16x8*)(lds + cur + kfo + 32 * KPITCH + s * 32);
;                 const bf16x8 q = *(const LAS bf16x8*)(ql + (6 + s) * 1024);
;                 p0 = __builtin_amdgcn_mfma_f32_32x32x16_bf16(a0, q, p0, 0, 0, 0); p1 = __builtin_amdgcn_mfma_f32_32x32x16_bf16(a1, q, p1, 0, 0, 0);
;             }
;             softmax_blk(p0, p1, ob0, ob1, mb, lb, pf, t == 0);
;             pv_blk(pf, ob0, ob1, lds + cur + vb);
;         }
;         *(LAS u32x4*)(lds + nxt + kd0) = ka; *(LAS u32x4*)(lds + (has1 ? nxt : 0u) + kd1) = kb; *(LAS u32x4*)(lds + nxt + vd) = va;
;         __syncthreads();
.Lmla_rescAp_back:
	v_exp_f32_e32 v64, v64
	v_exp_f32_e32 v65, v65
	v_exp_f32_e32 v66, v66
	v_exp_f32_e32 v67, v67
	v_exp_f32_e32 v68, v68
	v_exp_f32_e32 v69, v69
	s_waitcnt lgkmcnt(3)
	v_mfma_f32_32x32x16_bf16 v[96:111], v[176:179], v[186:189], v[96:111]
	v_mfma_f32_32x32x16_bf16 v[112:127], v[180:183], v[186:189], v[112:127]
	ds_read_b128 v[176:179], v155 offset:160
	ds_read_b128 v[180:183], v155 offset:6816
	ds_read_b128 v[186:189], v135 offset:54272
	v_exp_f32_e32 v70, v70
	v_exp_f32_e32 v71, v71
	v_add_f32_e32 v166, v64, v65
	v_add_f32_e32 v140, v140, v66
	v_add_f32_e32 v166, v166, v67
	v_cvt_pk_bf16_f32 v64, v64, v65
	v_cvt_pk_bf16_f32 v65, v66, v67
	v_exp_f32_e32 v72, v72
	v_exp_f32_e32 v73, v73
	v_exp_f32_e32 v74, v74
	v_exp_f32_e32 v75, v75
	v_add_f32_e32 v140, v140, v68
	v_add_f32_e32 v166, v166, v69
	v_add_f32_e32 v140, v140, v70
	v_add_f32_e32 v166, v166, v71
	v_cvt_pk_bf16_f32 v66, v68, v69
	v_cvt_pk_bf16_f32 v67, v70, v71
	v_exp_f32_e32 v76, v76
	v_exp_f32_e32 v77, v77
	v_exp_f32_e32 v78, v78
	v_exp_f32_e32 v79, v79
	v_add_f32_e32 v140, v140, v72
	v_add_f32_e32 v166, v166, v73
	s_waitcnt lgkmcnt(3)
	v_mfma_f32_32x32x16_bf16 v[96:111], v[128:131], v[162:165], v[96:111]
	v_mfma_f32_32x32x16_bf16 v[112:127], v[142:145], v[162:165], v[112:127]
	v_add_f32_e32 v140, v140, v74
	v_add_f32_e32 v166, v166, v75
	v_cvt_pk_bf16_f32 v68, v72, v73
	v_cvt_pk_bf16_f32 v69, v74, v75
	v_exp_f32_e32 v80, v80
	v_exp_f32_e32 v81, v81
	v_exp_f32_e32 v82, v82
	v_exp_f32_e32 v83, v83
	v_add_f32_e32 v140, v140, v76
	v_add_f32_e32 v166, v166, v77
	v_add_f32_e32 v140, v140, v78
	v_add_f32_e32 v166, v166, v79
	v_cvt_pk_bf16_f32 v70, v76, v77
	v_cvt_pk_bf16_f32 v71, v78, v79
	v_exp_f32_e32 v84, v84
	v_exp_f32_e32 v85, v85
	v_exp_f32_e32 v86, v86
	v_exp_f32_e32 v87, v87
	v_add_f32_e32 v140, v140, v80
	v_add_f32_e32 v166, v166, v81
	v_add_f32_e32 v140, v140, v82
	v_add_f32_e32 v166, v166, v83
	v_cvt_pk_bf16_f32 v72, v80, v81
	v_cvt_pk_bf16_f32 v73, v82, v83
	v_exp_f32_e32 v88, v88
	s_waitcnt lgkmcnt(0)
	v_mfma_f32_32x32x16_bf16 v[96:111], v[176:179], v[186:189], v[96:111]
	v_mfma_f32_32x32x16_bf16 v[112:127], v[180:183], v[186:189], v[112:127]
	v_exp_f32_e32 v89, v89
	v_exp_f32_e32 v90, v90
	v_exp_f32_e32 v91, v91
	v_add_f32_e32 v140, v140, v84
	v_add_f32_e32 v166, v166, v85
	v_add_f32_e32 v140, v140, v86
	v_add_f32_e32 v166, v166, v87
	v_cvt_pk_bf16_f32 v74, v84, v85
	v_cvt_pk_bf16_f32 v75, v86, v87
	v_exp_f32_e32 v92, v92
	v_exp_f32_e32 v93, v93
	v_exp_f32_e32 v94, v94
	v_exp_f32_e32 v95, v95
	v_add_f32_e32 v140, v140, v88
	v_add_f32_e32 v166, v166, v89
	v_add_f32_e32 v140, v140, v90
	v_add_f32_e32 v166, v166, v91
	v_cvt_pk_bf16_f32 v76, v88, v89
	v_cvt_pk_bf16_f32 v77, v90, v91
	v_add_f32_e32 v140, v140, v92
	v_add_f32_e32 v166, v166, v93
	v_add_f32_e32 v140, v140, v94
	v_add_f32_e32 v166, v166, v95
	v_cvt_pk_bf16_f32 v78, v92, v93
	v_cvt_pk_bf16_f32 v79, v94, v95
	v_add_f32_e32 v140, v140, v166
	s_nop 7
	s_nop 3
	v_max3_f32 v248, v96, v97, v98
	v_max3_f32 v249, v112, v113, v114
	v_max3_f32 v248, v248, v99, v100
	v_max3_f32 v249, v249, v115, v116
	v_max3_f32 v248, v248, v101, v102
	v_max3_f32 v249, v249, v117, v118
	v_max3_f32 v248, v248, v103, v104
	v_max3_f32 v249, v249, v119, v120
	v_max3_f32 v248, v248, v105, v106
	v_max3_f32 v249, v249, v121, v122
	v_max3_f32 v248, v248, v107, v108
	v_max3_f32 v249, v249, v123, v124
	v_max3_f32 v248, v248, v109, v110
	v_max3_f32 v249, v249, v125, v126
	v_max3_f32 v248, v248, v111, v127
	v_max_f32_e32 v248, v248, v249
	v_mov_b32_e32 v251, v248
	s_nop 1
	v_permlane32_swap_b32_e32 v248, v251
	v_max_f32_e32 v167, v248, v251
	v_sub_f32_e32 v96, v96, v167
	v_sub_f32_e32 v97, v97, v167
	v_sub_f32_e32 v98, v98, v167
	v_sub_f32_e32 v99, v99, v167
	v_sub_f32_e32 v100, v100, v167
	v_sub_f32_e32 v101, v101, v167
	v_sub_f32_e32 v102, v102, v167
	v_sub_f32_e32 v103, v103, v167
	v_sub_f32_e32 v104, v104, v167
	v_sub_f32_e32 v105, v105, v167
	v_sub_f32_e32 v106, v106, v167
	v_sub_f32_e32 v107, v107, v167
	v_sub_f32_e32 v108, v108, v167
	v_sub_f32_e32 v109, v109, v167
	v_sub_f32_e32 v110, v110, v167
	v_sub_f32_e32 v111, v111, v167
	v_sub_f32_e32 v112, v112, v167
	v_sub_f32_e32 v113, v113, v167
	v_sub_f32_e32 v114, v114, v167
	v_sub_f32_e32 v115, v115, v167
	v_sub_f32_e32 v116, v116, v167
	v_sub_f32_e32 v117, v117, v167
	v_sub_f32_e32 v118, v118, v167
	v_sub_f32_e32 v119, v119, v167
	v_sub_f32_e32 v120, v120, v167
	v_sub_f32_e32 v121, v121, v167
	v_sub_f32_e32 v122, v122, v167
	v_sub_f32_e32 v123, v123, v167
	v_sub_f32_e32 v124, v124, v167
	v_sub_f32_e32 v125, v125, v167
	v_sub_f32_e32 v126, v126, v167
	v_sub_f32_e32 v127, v127, v167
	v_sub_f32_e32 v190, 0, v167
	v_sub_f32_e32 v191, 0, v167
	v_sub_f32_e32 v192, 0, v167
	v_sub_f32_e32 v193, 0, v167
	v_sub_f32_e32 v194, 0, v167
	v_sub_f32_e32 v195, 0, v167
	v_sub_f32_e32 v196, 0, v167
	v_sub_f32_e32 v197, 0, v167
	v_sub_f32_e32 v198, 0, v167
	v_sub_f32_e32 v199, 0, v167
	v_sub_f32_e32 v200, 0, v167
	v_sub_f32_e32 v201, 0, v167
	v_sub_f32_e32 v202, 0, v167
	v_sub_f32_e32 v203, 0, v167
	v_sub_f32_e32 v204, 0, v167
	v_sub_f32_e32 v205, 0, v167
	s_waitcnt vmcnt(0)
	ds_write_b128 v150, v[218:221] offset:21504
	ds_write_b128 v159, v[222:225]
	s_waitcnt lgkmcnt(0)
	s_barrier
	s_nop 0
; #define LAS __attribute__((address_space(3)))
; __device__ __forceinline__ void softmax_blk(f32x16& p0, f32x16& p1, f32x16& o0, f32x16& o1, float& mhat, float& lrun, u32x4 (&pf)[4], bool first) {
;     float r0 = max2_(p0[0], p0[1]), r1 = max2_(p1[0], p1[1]);
; #pragma unroll
;     for (int e = 2; e < 16; ++e) { r0 = max2_(r0, p0[e]); r1 = max2_(r1, p1[e]); }
;     const float rm = swap_max(max2_(r0, r1));
;     if (first || __any(rm - mhat > THR)) {
;         const float mn = first ? rm : fmaxf(rm, mhat); const float f = first ? 0.f : __builtin_amdgcn_exp2f(mhat - mn); mhat = mn; lrun *= f;
; #pragma unroll
;         for (int e = 0; e < 16; ++e) { o0[e] *= f; o1[e] *= f; }
;     }
;     float s0 = 0.f, s1 = 0.f;
; #pragma unroll
;     for (int e = 0; e < 16; ++e) { p0[e] = __builtin_amdgcn_exp2f(p0[e] - mhat); p1[e] = __builtin_amdgcn_exp2f(p1[e] - mhat); s0 += p0[e]; s1 += p1[e]; }
;     lrun += s0 + s1;
;     pf[0] = MLA_PACK(p0, 0); pf[1] = MLA_PACK(p0, 8); pf[2] = MLA_PACK(p1, 0); pf[3] = MLA_PACK(p1, 8);
; }
; __device__ __forceinline__ void pv_blk(const u32x4 (&pf)[4], f32x16& o0, f32x16& o1, LAS const unsigned char* vbase) {
; #pragma unroll
;     for (int ks = 0; ks < 4; ++ks) {
;         const bf16x8 p = __builtin_bit_cast(bf16x8, pf[ks]);
;         { const s16x4 lo = vtr(vbase + ks * 1024), hh = vtr(vbase + ks * 1024 + 512); const bf16x8 vf = {lo[0], lo[1], lo[2], lo[3], hh[0], hh[1], hh[2], hh[3]};
;           o0 = __builtin_amdgcn_mfma_f32_32x32x16_bf16(vf, p, o0, 0, 0, 0); }
;         { const s16x4 lo = vtr(vbase + 4096 + ks * 1024), hh = vtr(vbase + 4096 + ks * 1024 + 512); const bf16x8 vf = {lo[0], lo[1], lo[2], lo[3], hh[0], hh[1], hh[2], hh[3]};
;           o1 = __builtin_amdgcn_mfma_f32_32x32x16_bf16(vf, p, o1, 0, 0, 0); }
;     }
; }
; __device__ __forceinline__ void attn_unit(const bf16_t* Qh, const bf16_t* Kh, const bf16_t* Vh, bf16_t* Oh  , int S, int qb, LAS unsigned char* lds, int tid) {
;     ...
;         ka = GLD(u32x4, Kg + (size_t)tn * 768 + kc0); kb = GLD(u32x4, Kg + (size_t)tn * 768 + kc1); va = GLD(u32x4, Vg + (size_t)tn * 512 + tid);
;         u32x4 pf[4];
;         {
;             f32x16 p0 = {}, p1 = {};
; #pragma unroll
;             for (int s = 0; s < 6; ++s) {
;                 const bf16x8 a0 = *(const LAS bf16x8*)(lds + cur + kfo + s * 32), a1 = *(const LAS bf16x8*)(lds + cur + kfo + 32 * KPITCH + s * 32);
.Lmla_top:
	ds_read_b64_tr_b16 v[128:129], v158 offset:13312
	ds_read_b64_tr_b16 v[130:131], v158 offset:13824
	ds_read_b64_tr_b16 v[142:143], v158 offset:17408
	ds_read_b64_tr_b16 v[144:145], v158 offset:17920
	ds_read_b64_tr_b16 v[176:177], v158 offset:14336
	ds_read_b64_tr_b16 v[178:179], v158 offset:14848
	ds_read_b64_tr_b16 v[180:181], v158 offset:18432
	ds_read_b64_tr_b16 v[182:183], v158 offset:18944
	s_waitcnt lgkmcnt(4)
	s_nop 0
	v_mfma_f32_32x32x16_bf16 v[16:31], v[128:131], v[64:67], v[16:31]
	v_mfma_f32_32x32x16_bf16 v[0:15], v[142:145], v[64:67], v[0:15]
	ds_read_b64_tr_b16 v[128:129], v158 offset:15360
	ds_read_b64_tr_b16 v[130:131], v158 offset:15872
	ds_read_b64_tr_b16 v[142:143], v158 offset:19456
	ds_read_b64_tr_b16 v[144:145], v158 offset:19968
	global_load_dwordx4 v[218:221], v171, s[26:27]
	global_load_dwordx4 v[222:225], v184, s[26:27]
	global_load_dwordx4 v[226:229], v146, s[100:101]
	s_add_u32 s26, s26, 0x3000
	s_addc_u32 s27, s27, 0
	s_nop 0
	s_add_u32 s100, s100, 0x2000
	s_addc_u32 s101, s101, 0
	s_waitcnt lgkmcnt(4)
	v_max3_f32 v248, v96, v97, v98
	v_max3_f32 v249, v112, v113, v114
	v_max3_f32 v248, v248, v99, v100
	v_max3_f32 v249, v249, v115, v116
	v_max3_f32 v248, v248, v101, v102
	v_max3_f32 v249, v249, v117, v118
	v_max3_f32 v248, v248, v103, v104
	v_max3_f32 v249, v249, v119, v120
	v_max3_f32 v248, v248, v105, v106
	v_max3_f32 v249, v249, v121, v122
	v_max3_f32 v248, v248, v107, v108
	v_max3_f32 v249, v249, v123, v124
	v_max3_f32 v248, v248, v109, v110
	v_max3_f32 v249, v249, v125, v126
	v_mfma_f32_32x32x16_bf16 v[16:31], v[176:179], v[68:71], v[16:31]
	v_mfma_f32_32x32x16_bf16 v[0:15], v[180:183], v[68:71], v[0:15]
	ds_read_b64_tr_b16 v[176:177], v158 offset:16384
	ds_read_b64_tr_b16 v[178:179], v158 offset:16896
	ds_read_b64_tr_b16 v[180:181], v158 offset:20480
	ds_read_b64_tr_b16 v[182:183], v158 offset:20992
	v_max3_f32 v248, v248, v111, v127
	v_max_f32_e64 v248, v248, v249
	v_mov_b32_e32 v251, v248
	s_nop 1
	v_permlane32_swap_b32_e32 v248, v251
	v_max_f32_e32 v167, v248, v251
	v_cmp_lt_f32_e32 vcc, s72, v167
	s_cbranch_vccnz .Lmla_rescBo
.Lmla_rescBo_back:
	v_exp_f32_e32 v96, v96
	v_exp_f32_e32 v97, v97
	v_exp_f32_e32 v98, v98
	s_waitcnt lgkmcnt(4)
	v_mfma_f32_32x32x16_bf16 v[16:31], v[128:131], v[72:75], v[16:31]
	v_mfma_f32_32x32x16_bf16 v[0:15], v[142:145], v[72:75], v[0:15]
	ds_read_b128 v[128:131], v155 offset:21504
	ds_read_b128 v[142:145], v155 offset:28160
	ds_read_b128 v[162:165], v135 offset:43008
	v_exp_f32_e64 v99, v99
	v_exp_f32_e32 v100, v100
	v_exp_f32_e32 v101, v101
	v_exp_f32_e32 v102, v102
	v_exp_f32_e32 v103, v103
	v_add_f32_e32 v166, v96, v97
	v_add_f32_e32 v141, v141, v98
	v_add_f32_e32 v166, v166, v99
	s_waitcnt lgkmcnt(3)
	v_mfma_f32_32x32x16_bf16 v[16:31], v[176:179], v[76:79], v[16:31]
	v_mfma_f32_32x32x16_bf16 v[0:15], v[180:183], v[76:79], v[0:15]
	ds_read_b128 v[176:179], v155 offset:21536
	ds_read_b128 v[180:183], v155 offset:28192
	ds_read_b128 v[186:189], v135 offset:44032
	v_cvt_pk_bf16_f32 v96, v96, v97
	v_cvt_pk_bf16_f32 v97, v98, v99
	v_exp_f32_e32 v104, v104
	v_exp_f32_e32 v105, v105
	v_exp_f32_e32 v106, v106
	v_exp_f32_e32 v107, v107
	v_add_f32_e32 v141, v141, v100
	v_add_f32_e32 v166, v166, v101
	v_add_f32_e32 v141, v141, v102
	s_waitcnt lgkmcnt(3)
	v_mfma_f32_32x32x16_bf16 v[64:79], v[128:131], v[162:165], v[232:247]
	v_mfma_f32_32x32x16_bf16 v[80:95], v[142:145], v[162:165], v[232:247]
	ds_read_b128 v[128:131], v155 offset:21568
	ds_read_b128 v[142:145], v155 offset:28224
	ds_read_b128 v[162:165], v135 offset:45056
	v_add_f32_e64 v166, v166, v103
	v_cvt_pk_bf16_f32 v98, v100, v101
	v_cvt_pk_bf16_f32 v99, v102, v103
	v_exp_f32_e64 v108, v108
	v_exp_f32_e32 v109, v109
	v_exp_f32_e32 v110, v110
	v_exp_f32_e32 v111, v111
	v_add_f32_e32 v141, v141, v104
	v_add_f32_e32 v166, v166, v105
	s_waitcnt lgkmcnt(3)
	v_mfma_f32_32x32x16_bf16 v[64:79], v[176:179], v[186:189], v[64:79]
	v_mfma_f32_32x32x16_bf16 v[80:95], v[180:183], v[186:189], v[80:95]
	ds_read_b128 v[176:179], v155 offset:21600
	ds_read_b128 v[180:183], v155 offset:28256
	ds_read_b128 v[186:189], v135 offset:46080
	v_add_f32_e32 v141, v141, v106
	v_add_f32_e32 v166, v166, v107
	v_cvt_pk_bf16_f32 v100, v104, v105
	v_cvt_pk_bf16_f32 v101, v106, v107
	v_exp_f32_e64 v112, v112
	v_exp_f32_e32 v113, v113
	v_exp_f32_e32 v114, v114
	v_exp_f32_e32 v115, v115
	v_add_f32_e32 v141, v141, v108
	v_add_f32_e32 v166, v166, v109
	s_waitcnt lgkmcnt(3)
	v_mfma_f32_32x32x16_bf16 v[64:79], v[128:131], v[162:165], v[64:79]
	v_mfma_f32_32x32x16_bf16 v[80:95], v[142:145], v[162:165], v[80:95]
	ds_read_b128 v[128:131], v155 offset:21632
	ds_read_b128 v[142:145], v155 offset:28288
	ds_read_b128 v[162:165], v135 offset:47104
	v_add_f32_e32 v141, v141, v110
	v_add_f32_e32 v166, v166, v111
	v_cvt_pk_bf16_f32 v102, v108, v109
	v_cvt_pk_bf16_f32 v103, v110, v111
	v_exp_f32_e32 v116, v116
	v_exp_f32_e32 v117, v117
	v_exp_f32_e32 v118, v118
	v_exp_f32_e32 v119, v119
	v_add_f32_e32 v141, v141, v112
	s_waitcnt lgkmcnt(3)
	v_mfma_f32_32x32x16_bf16 v[64:79], v[176:179], v[186:189], v[64:79]
	v_mfma_f32_32x32x16_bf16 v[80:95], v[180:183], v[186:189], v[80:95]
	ds_read_b128 v[176:179], v155 offset:21664
	ds_read_b128 v[180:183], v155 offset:28320
	ds_read_b128 v[186:189], v135 offset:48128
	v_add_f32_e64 v166, v166, v113
	v_add_f32_e32 v141, v141, v114
	v_add_f32_e32 v166, v166, v115
	v_cvt_pk_bf16_f32 v104, v112, v113
	v_cvt_pk_bf16_f32 v105, v114, v115
	v_exp_f32_e32 v120, v120
	v_exp_f32_e32 v121, v121
	v_exp_f32_e32 v122, v122
	v_exp_f32_e32 v123, v123
	v_add_f32_e32 v141, v141, v116
	s_waitcnt lgkmcnt(3)
; #define LAS __attribute__((address_space(3)))
; __device__ __forceinline__ void softmax_blk(f32x16& p0, f32x16& p1, f32x16& o0, f32x16& o1, float& mhat, float& lrun, u32x4 (&pf)[4], bool first) {
;     float r0 = max2_(p0[0], p0[1]), r1 = max2_(p1[0], p1[1]);
; #pragma unroll
;     for (int e = 2; e < 16; ++e) { r0 = max2_(r0, p0[e]); r1 = max2_(r1, p1[e]); }
;     const float rm = swap_max(max2_(r0, r1));
;     if (first || __any(rm - mhat > THR)) {
;         const float mn = first ? rm : fmaxf(rm, mhat); const float f = first ? 0.f : __builtin_amdgcn_exp2f(mhat - mn); mhat = mn; lrun *= f;
; #pragma unroll
;         for (int e = 0; e < 16; ++e) { o0[e] *= f; o1[e] *= f; }
;     }
;     float s0 = 0.f, s1 = 0.f;
; #pragma unroll
;     for (int e = 0; e < 16; ++e) { p0[e] = __builtin_amdgcn_exp2f(p0[e] - mhat); p1[e] = __builtin_amdgcn_exp2f(p1[e] - mhat); s0 += p0[e]; s1 += p1[e]; }
;     lrun += s0 + s1;
;     pf[0] = MLA_PACK(p0, 0); pf[1] = MLA_PACK(p0, 8); pf[2] = MLA_PACK(p1, 0); pf[3] = MLA_PACK(p1, 8);
; }
; __device__ __forceinline__ void pv_blk(const u32x4 (&pf)[4], f32x16& o0, f32x16& o1, LAS const unsigned char* vbase) {
; #pragma unroll
;     for (int ks = 0; ks < 4; ++ks) {
;         const bf16x8 p = __builtin_bit_cast(bf16x8, pf[ks]);
;         { const s16x4 lo = vtr(vbase + ks * 1024), hh = vtr(vbase + ks * 1024 + 512); const bf16x8 vf = {lo[0], lo[1], lo[2], lo[3], hh[0], hh[1], hh[2], hh[3]};
;           o0 = __builtin_amdgcn_mfma_f32_32x32x16_bf16(vf, p, o0, 0, 0, 0); }
;         { const s16x4 lo = vtr(vbase + 4096 + ks * 1024), hh = vtr(vbase + 4096 + ks * 1024 + 512); const bf16x8 vf = {lo[0], lo[1], lo[2], lo[3], hh[0], hh[1], hh[2], hh[3]};
;           o1 = __builtin_amdgcn_mfma_f32_32x32x16_bf16(vf, p, o1, 0, 0, 0); }
;     }
; }
; __device__ __forceinline__ void attn_unit(const bf16_t* Qh, const bf16_t* Kh, const bf16_t* Vh, bf16_t* Oh  , int S, int qb, LAS unsigned char* lds, int tid) {
;     ...
;         ka = GLD(u32x4, Kg + (size_t)tn * 768 + kc0); kb = GLD(u32x4, Kg + (size_t)tn * 768 + kc1); va = GLD(u32x4, Vg + (size_t)tn * 512 + tid);
;         u32x4 pf[4];
;         {
;             f32x16 p0 = {}, p1 = {};
; #pragma unroll
;             for (int s = 0; s < 6; ++s) {
;                 const bf16x8 a0 = *(const LAS bf16x8*)(lds + cur + kfo + s * 32), a1 = *(const LAS bf16x8*)(lds + cur + kfo + 32 * KPITCH + s * 32);
	v_mfma_f32_32x32x16_bf16 v[64:79], v[128:131], v[162:165], v[64:79]
	v_mfma_f32_32x32x16_bf16 v[80:95], v[142:145], v[162:165], v[80:95]
	ds_read_b64_tr_b16 v[128:129], v158 offset:13312
	ds_read_b64_tr_b16 v[130:131], v158 offset:13824
	ds_read_b64_tr_b16 v[142:143], v158 offset:17408
	ds_read_b64_tr_b16 v[144:145], v158 offset:17920
	v_add_f32_e64 v166, v166, v117
	v_add_f32_e32 v141, v141, v118
	v_add_f32_e32 v166, v166, v119
	v_cvt_pk_bf16_f32 v106, v116, v117
	v_cvt_pk_bf16_f32 v107, v118, v119
	v_exp_f32_e64 v124, v124
	v_exp_f32_e32 v125, v125
	v_exp_f32_e32 v126, v126
	v_exp_f32_e32 v127, v127
	s_waitcnt lgkmcnt(4)
	v_mfma_f32_32x32x16_bf16 v[64:79], v[176:179], v[186:189], v[64:79]
	v_mfma_f32_32x32x16_bf16 v[80:95], v[180:183], v[186:189], v[80:95]
	ds_read_b64_tr_b16 v[176:177], v158 offset:14336
	ds_read_b64_tr_b16 v[178:179], v158 offset:14848
	ds_read_b64_tr_b16 v[180:181], v158 offset:18432
	ds_read_b64_tr_b16 v[182:183], v158 offset:18944
	v_add_f32_e32 v141, v141, v120
	v_add_f32_e32 v166, v166, v121
	v_add_f32_e32 v141, v141, v122
	v_add_f32_e32 v166, v166, v123
	v_cvt_pk_bf16_f32 v108, v120, v121
	v_cvt_pk_bf16_f32 v109, v122, v123
	v_add_f32_e32 v141, v141, v124
	v_add_f32_e32 v166, v166, v125
	v_add_f32_e32 v141, v141, v126
	v_add_f32_e32 v166, v166, v127
	v_cvt_pk_bf16_f32 v110, v124, v125
	v_cvt_pk_bf16_f32 v111, v126, v127
	v_add_f32_e32 v141, v141, v166
	s_waitcnt lgkmcnt(4)
	v_mfma_f32_32x32x16_bf16 v[48:63], v[128:131], v[96:99], v[48:63]
	v_mfma_f32_32x32x16_bf16 v[32:47], v[142:145], v[96:99], v[32:47]
	ds_read_b64_tr_b16 v[128:129], v158 offset:15360
	ds_read_b64_tr_b16 v[130:131], v158 offset:15872
	ds_read_b64_tr_b16 v[142:143], v158 offset:19456
	ds_read_b64_tr_b16 v[144:145], v158 offset:19968
	v_max3_f32 v248, v64, v65, v66
	v_max3_f32 v249, v80, v81, v82
	v_max3_f32 v248, v248, v67, v68
	v_max3_f32 v249, v249, v83, v84
	v_max3_f32 v248, v248, v69, v70
	v_max3_f32 v249, v249, v85, v86
	v_max3_f32 v248, v248, v71, v72
	v_max3_f32 v249, v249, v87, v88
	v_max3_f32 v248, v248, v73, v74
	v_max3_f32 v249, v249, v89, v90
	v_max3_f32 v248, v248, v75, v76
	v_max3_f32 v249, v249, v91, v92
	v_max3_f32 v248, v248, v77, v78
	v_max3_f32 v249, v249, v93, v94
	s_waitcnt lgkmcnt(4)
	s_nop 0
	v_mfma_f32_32x32x16_bf16 v[48:63], v[176:179], v[100:103], v[48:63]
	v_mfma_f32_32x32x16_bf16 v[32:47], v[180:183], v[100:103], v[32:47]
	ds_read_b64_tr_b16 v[176:177], v158 offset:16384
	ds_read_b64_tr_b16 v[178:179], v158 offset:16896
	ds_read_b64_tr_b16 v[180:181], v158 offset:20480
	ds_read_b64_tr_b16 v[182:183], v158 offset:20992
	v_max3_f32 v248, v248, v79, v95
	v_max_f32_e64 v248, v248, v249
	v_mov_b32_e32 v251, v248
	s_nop 1
	v_permlane32_swap_b32_e32 v248, v251
	v_max_f32_e32 v167, v248, v251
	v_cmp_lt_f32_e32 vcc, s72, v167
	s_cbranch_vccnz .Lmla_rescAo
.Lmla_rescAo_back:
	v_exp_f32_e32 v64, v64
	v_exp_f32_e32 v65, v65
	v_exp_f32_e32 v66, v66
	s_waitcnt lgkmcnt(4)
	v_mfma_f32_32x32x16_bf16 v[48:63], v[128:131], v[104:107], v[48:63]
	v_mfma_f32_32x32x16_bf16 v[32:47], v[142:145], v[104:107], v[32:47]
	ds_read_b128 v[128:131], v155 offset:21504
	ds_read_b128 v[142:145], v155 offset:28160
	ds_read_b128 v[162:165], v135 offset:49152
	v_exp_f32_e64 v67, v67
	v_exp_f32_e32 v68, v68
	v_exp_f32_e32 v69, v69
	v_exp_f32_e32 v70, v70
	v_exp_f32_e32 v71, v71
	v_add_f32_e32 v166, v64, v65
	v_add_f32_e32 v140, v140, v66
	v_add_f32_e32 v166, v166, v67
	s_waitcnt lgkmcnt(3)
	v_mfma_f32_32x32x16_bf16 v[48:63], v[176:179], v[108:111], v[48:63]
	v_mfma_f32_32x32x16_bf16 v[32:47], v[180:183], v[108:111], v[32:47]
	ds_read_b128 v[176:179], v155 offset:21536
	ds_read_b128 v[180:183], v155 offset:28192
	ds_read_b128 v[186:189], v135 offset:50176
	v_cvt_pk_bf16_f32 v64, v64, v65
	v_cvt_pk_bf16_f32 v65, v66, v67
	v_exp_f32_e32 v72, v72
	v_exp_f32_e32 v73, v73
	v_exp_f32_e32 v74, v74
	v_exp_f32_e32 v75, v75
	v_add_f32_e32 v140, v140, v68
	v_add_f32_e32 v166, v166, v69
	v_add_f32_e32 v140, v140, v70
	s_waitcnt lgkmcnt(3)
	v_mfma_f32_32x32x16_bf16 v[96:111], v[128:131], v[162:165], v[190:205]
	v_mfma_f32_32x32x16_bf16 v[112:127], v[142:145], v[162:165], v[190:205]
	ds_read_b128 v[128:131], v155 offset:21568
	ds_read_b128 v[142:145], v155 offset:28224
	ds_read_b128 v[162:165], v135 offset:51200
	v_add_f32_e64 v166, v166, v71
	v_cvt_pk_bf16_f32 v66, v68, v69
	v_cvt_pk_bf16_f32 v67, v70, v71
	v_exp_f32_e64 v76, v76
	v_exp_f32_e32 v77, v77
	v_exp_f32_e32 v78, v78
	v_exp_f32_e32 v79, v79
	v_add_f32_e32 v140, v140, v72
	v_add_f32_e32 v166, v166, v73
	s_waitcnt lgkmcnt(3)
	v_mfma_f32_32x32x16_bf16 v[96:111], v[176:179], v[186:189], v[96:111]
	v_mfma_f32_32x32x16_bf16 v[112:127], v[180:183], v[186:189], v[112:127]
	ds_read_b128 v[176:179], v155 offset:21600
	ds_read_b128 v[180:183], v155 offset:28256
	ds_read_b128 v[186:189], v135 offset:52224
	v_add_f32_e32 v140, v140, v74
	v_add_f32_e32 v166, v166, v75
	v_cvt_pk_bf16_f32 v68, v72, v73
	v_cvt_pk_bf16_f32 v69, v74, v75
	v_exp_f32_e64 v80, v80
	v_exp_f32_e32 v81, v81
	v_exp_f32_e32 v82, v82
	v_exp_f32_e32 v83, v83
	v_add_f32_e32 v140, v140, v76
	v_add_f32_e32 v166, v166, v77
	s_waitcnt lgkmcnt(3)
	v_mfma_f32_32x32x16_bf16 v[96:111], v[128:131], v[162:165], v[96:111]
	v_mfma_f32_32x32x16_bf16 v[112:127], v[142:145], v[162:165], v[112:127]
	ds_read_b128 v[128:131], v155 offset:21632
	ds_read_b128 v[142:145], v155 offset:28288
	ds_read_b128 v[162:165], v135 offset:53248
	v_add_f32_e32 v140, v140, v78
	v_add_f32_e32 v166, v166, v79
	v_cvt_pk_bf16_f32 v70, v76, v77
	v_cvt_pk_bf16_f32 v71, v78, v79
	v_exp_f32_e32 v84, v84
	v_exp_f32_e32 v85, v85
	v_exp_f32_e32 v86, v86
	v_exp_f32_e32 v87, v87
	v_add_f32_e32 v140, v140, v80
	s_waitcnt lgkmcnt(3)
; #define LAS __attribute__((address_space(3)))
; __device__ __forceinline__ void softmax_blk(f32x16& p0, f32x16& p1, f32x16& o0, f32x16& o1, float& mhat, float& lrun, u32x4 (&pf)[4], bool first) {
;     float r0 = max2_(p0[0], p0[1]), r1 = max2_(p1[0], p1[1]);
; #pragma unroll
;     for (int e = 2; e < 16; ++e) { r0 = max2_(r0, p0[e]); r1 = max2_(r1, p1[e]); }
;     const float rm = swap_max(max2_(r0, r1));
;     if (first || __any(rm - mhat > THR)) {
;         const float mn = first ? rm : fmaxf(rm, mhat); const float f = first ? 0.f : __builtin_amdgcn_exp2f(mhat - mn); mhat = mn; lrun *= f;
; #pragma unroll
;         for (int e = 0; e < 16; ++e) { o0[e] *= f; o1[e] *= f; }
;     }
;     float s0 = 0.f, s1 = 0.f;
; #pragma unroll
;     for (int e = 0; e < 16; ++e) { p0[e] = __builtin_amdgcn_exp2f(p0[e] - mhat); p1[e] = __builtin_amdgcn_exp2f(p1[e] - mhat); s0 += p0[e]; s1 += p1[e]; }
;     lrun += s0 + s1;
;     pf[0] = MLA_PACK(p0, 0); pf[1] = MLA_PACK(p0, 8); pf[2] = MLA_PACK(p1, 0); pf[3] = MLA_PACK(p1, 8);
; }
; __device__ __forceinline__ void pv_blk(const u32x4 (&pf)[4], f32x16& o0, f32x16& o1, LAS const unsigned char* vbase) {
; #pragma unroll
;     for (int ks = 0; ks < 4; ++ks) {
;         const bf16x8 p = __builtin_bit_cast(bf16x8, pf[ks]);
;         { const s16x4 lo = vtr(vbase + ks * 1024), hh = vtr(vbase + ks * 1024 + 512); const bf16x8 vf = {lo[0], lo[1], lo[2], lo[3], hh[0], hh[1], hh[2], hh[3]};
;           o0 = __builtin_amdgcn_mfma_f32_32x32x16_bf16(vf, p, o0, 0, 0, 0); }
;         { const s16x4 lo = vtr(vbase + 4096 + ks * 1024), hh = vtr(vbase + 4096 + ks * 1024 + 512); const bf16x8 vf = {lo[0], lo[1], lo[2], lo[3], hh[0], hh[1], hh[2], hh[3]};
;           o1 = __builtin_amdgcn_mfma_f32_32x32x16_bf16(vf, p, o1, 0, 0, 0); }
;     }
; }
; __device__ __forceinline__ void attn_unit(const bf16_t* Qh, const bf16_t* Kh, const bf16_t* Vh, bf16_t* Oh  , int S, int qb, LAS unsigned char* lds, int tid) {
;     ...
;     for (int t = 0; t < NT; ++t) {
;         const unsigned cur = (unsigned)(t & 1) * BUF, nxt = BUF - cur;
;         const int tn = t + 1 < NT ? t + 1 : t;
;         ka = GLD(u32x4, Kg + (size_t)tn * 768 + kc0); kb = GLD(u32x4, Kg + (size_t)tn * 768 + kc1); va = GLD(u32x4, Vg + (size_t)tn * 512 + tid);
;         u32x4 pf[4];
;         {
;             f32x16 p0 = {}, p1 = {};
; #pragma unroll
;             for (int s = 0; s < 6; ++s) {
	v_mfma_f32_32x32x16_bf16 v[96:111], v[176:179], v[186:189], v[96:111]
	v_mfma_f32_32x32x16_bf16 v[112:127], v[180:183], v[186:189], v[112:127]
	ds_read_b128 v[176:179], v155 offset:21664
	ds_read_b128 v[180:183], v155 offset:28320
	ds_read_b128 v[186:189], v135 offset:54272
	v_add_f32_e64 v166, v166, v81
	v_add_f32_e32 v140, v140, v82
	v_add_f32_e32 v166, v166, v83
	v_cvt_pk_bf16_f32 v72, v80, v81
	v_cvt_pk_bf16_f32 v73, v82, v83
	v_exp_f32_e32 v88, v88
	v_exp_f32_e32 v89, v89
	v_exp_f32_e32 v90, v90
	v_exp_f32_e32 v91, v91
	v_add_f32_e32 v140, v140, v84
	s_waitcnt vmcnt(0)
	ds_write_b128 v150, v[218:221]
	ds_write_b128 v156, v[222:225]
	ds_write_b128 v157, v[226:229] offset:34816
	s_waitcnt lgkmcnt(6)
	s_nop 0
	v_mfma_f32_32x32x16_bf16 v[96:111], v[128:131], v[162:165], v[96:111]
	v_mfma_f32_32x32x16_bf16 v[112:127], v[142:145], v[162:165], v[112:127]
	v_add_f32_e64 v166, v166, v85
	v_add_f32_e32 v140, v140, v86
	v_add_f32_e32 v166, v166, v87
	v_cvt_pk_bf16_f32 v74, v84, v85
	v_cvt_pk_bf16_f32 v75, v86, v87
	v_exp_f32_e64 v92, v92
	v_exp_f32_e32 v93, v93
	v_exp_f32_e32 v94, v94
	v_exp_f32_e32 v95, v95
	s_waitcnt lgkmcnt(3)
	v_mfma_f32_32x32x16_bf16 v[96:111], v[176:179], v[186:189], v[96:111]
	v_mfma_f32_32x32x16_bf16 v[112:127], v[180:183], v[186:189], v[112:127]
	v_add_f32_e32 v140, v140, v88
	v_add_f32_e32 v166, v166, v89
	v_add_f32_e32 v140, v140, v90
	v_add_f32_e32 v166, v166, v91
	v_cvt_pk_bf16_f32 v76, v88, v89
	v_cvt_pk_bf16_f32 v77, v90, v91
	v_add_f32_e32 v140, v140, v92
	v_add_f32_e32 v166, v166, v93
	v_add_f32_e32 v140, v140, v94
	v_add_f32_e32 v166, v166, v95
	v_cvt_pk_bf16_f32 v78, v92, v93
	v_cvt_pk_bf16_f32 v79, v94, v95
	v_add_f32_e32 v140, v140, v166
	s_waitcnt lgkmcnt(0)
	s_barrier
	s_add_i32 s1, s1, 1
	s_cmp_lg_u32 s1, s18
	s_cbranch_scc0 .Lmla_epi
	ds_read_b64_tr_b16 v[128:129], v158 offset:34816
	ds_read_b64_tr_b16 v[130:131], v158 offset:35328
	ds_read_b64_tr_b16 v[142:143], v158 offset:38912
	ds_read_b64_tr_b16 v[144:145], v158 offset:39424
	ds_read_b64_tr_b16 v[176:177], v158 offset:35840
	ds_read_b64_tr_b16 v[178:179], v158 offset:36352
	ds_read_b64_tr_b16 v[180:181], v158 offset:39936
	ds_read_b64_tr_b16 v[182:183], v158 offset:40448
	s_waitcnt lgkmcnt(4)
	s_nop 0
	v_mfma_f32_32x32x16_bf16 v[16:31], v[128:131], v[64:67], v[16:31]
	v_mfma_f32_32x32x16_bf16 v[0:15], v[142:145], v[64:67], v[0:15]
	ds_read_b64_tr_b16 v[128:129], v158 offset:36864
	ds_read_b64_tr_b16 v[130:131], v158 offset:37376
	ds_read_b64_tr_b16 v[142:143], v158 offset:40960
	ds_read_b64_tr_b16 v[144:145], v158 offset:41472
	global_load_dwordx4 v[218:221], v171, s[26:27]
	global_load_dwordx4 v[222:225], v184, s[26:27]
	global_load_dwordx4 v[226:229], v146, s[100:101]
	s_add_u32 s26, s26, 0x3000
	s_addc_u32 s27, s27, 0
	s_nop 0
	s_add_u32 s100, s100, 0x2000
	s_addc_u32 s101, s101, 0
	s_waitcnt lgkmcnt(4)
	v_max3_f32 v248, v96, v97, v98
	v_max3_f32 v249, v112, v113, v114
	v_max3_f32 v248, v248, v99, v100
	v_max3_f32 v249, v249, v115, v116
	v_max3_f32 v248, v248, v101, v102
	v_max3_f32 v249, v249, v117, v118
	v_max3_f32 v248, v248, v103, v104
	v_max3_f32 v249, v249, v119, v120
	v_max3_f32 v248, v248, v105, v106
	v_max3_f32 v249, v249, v121, v122
	v_max3_f32 v248, v248, v107, v108
	v_max3_f32 v249, v249, v123, v124
	v_max3_f32 v248, v248, v109, v110
	v_max3_f32 v249, v249, v125, v126
	v_mfma_f32_32x32x16_bf16 v[16:31], v[176:179], v[68:71], v[16:31]
	v_mfma_f32_32x32x16_bf16 v[0:15], v[180:183], v[68:71], v[0:15]
	ds_read_b64_tr_b16 v[176:177], v158 offset:37888
	ds_read_b64_tr_b16 v[178:179], v158 offset:38400
	ds_read_b64_tr_b16 v[180:181], v158 offset:41984
	ds_read_b64_tr_b16 v[182:183], v158 offset:42496
	v_max3_f32 v248, v248, v111, v127
	v_max_f32_e64 v248, v248, v249
	v_mov_b32_e32 v251, v248
	s_nop 1
	v_permlane32_swap_b32_e32 v248, v251
	v_max_f32_e32 v167, v248, v251
	v_cmp_lt_f32_e32 vcc, s72, v167
	s_cbranch_vccnz .Lmla_rescBv
.Lmla_rescBv_back:
	v_exp_f32_e32 v96, v96
	v_exp_f32_e32 v97, v97
	v_exp_f32_e32 v98, v98
	s_waitcnt lgkmcnt(4)
	v_mfma_f32_32x32x16_bf16 v[16:31], v[128:131], v[72:75], v[16:31]
	v_mfma_f32_32x32x16_bf16 v[0:15], v[142:145], v[72:75], v[0:15]
	ds_read_b128 v[128:131], v155
	ds_read_b128 v[142:145], v155 offset:6656
	ds_read_b128 v[162:165], v135 offset:43008
	v_exp_f32_e64 v99, v99
	v_exp_f32_e32 v100, v100
	v_exp_f32_e32 v101, v101
	v_exp_f32_e32 v102, v102
	v_exp_f32_e32 v103, v103
	v_add_f32_e32 v166, v96, v97
	v_add_f32_e32 v141, v141, v98
	v_add_f32_e32 v166, v166, v99
	s_waitcnt lgkmcnt(3)
	v_mfma_f32_32x32x16_bf16 v[16:31], v[176:179], v[76:79], v[16:31]
	v_mfma_f32_32x32x16_bf16 v[0:15], v[180:183], v[76:79], v[0:15]
	ds_read_b128 v[176:179], v155 offset:32
	ds_read_b128 v[180:183], v155 offset:6688
	ds_read_b128 v[186:189], v135 offset:44032
	v_cvt_pk_bf16_f32 v96, v96, v97
	v_cvt_pk_bf16_f32 v97, v98, v99
	v_exp_f32_e32 v104, v104
	v_exp_f32_e32 v105, v105
	v_exp_f32_e32 v106, v106
	v_exp_f32_e32 v107, v107
	v_add_f32_e32 v141, v141, v100
	v_add_f32_e32 v166, v166, v101
	v_add_f32_e32 v141, v141, v102
	s_waitcnt lgkmcnt(3)
	v_mfma_f32_32x32x16_bf16 v[64:79], v[128:131], v[162:165], v[232:247]
	v_mfma_f32_32x32x16_bf16 v[80:95], v[142:145], v[162:165], v[232:247]
	ds_read_b128 v[128:131], v155 offset:64
	ds_read_b128 v[142:145], v155 offset:6720
	ds_read_b128 v[162:165], v135 offset:45056
	v_add_f32_e64 v166, v166, v103
	v_cvt_pk_bf16_f32 v98, v100, v101
	v_cvt_pk_bf16_f32 v99, v102, v103
	v_exp_f32_e64 v108, v108
	v_exp_f32_e32 v109, v109
	v_exp_f32_e32 v110, v110
	v_exp_f32_e32 v111, v111
	v_add_f32_e32 v141, v141, v104
	v_add_f32_e32 v166, v166, v105
	s_waitcnt lgkmcnt(3)
; #define LAS __attribute__((address_space(3)))
; __device__ __forceinline__ void softmax_blk(f32x16& p0, f32x16& p1, f32x16& o0, f32x16& o1, float& mhat, float& lrun, u32x4 (&pf)[4], bool first) {
;     float r0 = max2_(p0[0], p0[1]), r1 = max2_(p1[0], p1[1]);
; #pragma unroll
;     for (int e = 2; e < 16; ++e) { r0 = max2_(r0, p0[e]); r1 = max2_(r1, p1[e]); }
;     const float rm = swap_max(max2_(r0, r1));
;     if (first || __any(rm - mhat > THR)) {
;         const float mn = first ? rm : fmaxf(rm, mhat); const float f = first ? 0.f : __builtin_amdgcn_exp2f(mhat - mn); mhat = mn; lrun *= f;
; #pragma unroll
;         for (int e = 0; e < 16; ++e) { o0[e] *= f; o1[e] *= f; }
;     }
;     float s0 = 0.f, s1 = 0.f;
; #pragma unroll
;     for (int e = 0; e < 16; ++e) { p0[e] = __builtin_amdgcn_exp2f(p0[e] - mhat); p1[e] = __builtin_amdgcn_exp2f(p1[e] - mhat); s0 += p0[e]; s1 += p1[e]; }
;     lrun += s0 + s1;
;     pf[0] = MLA_PACK(p0, 0); pf[1] = MLA_PACK(p0, 8); pf[2] = MLA_PACK(p1, 0); pf[3] = MLA_PACK(p1, 8);
; }
; __device__ __forceinline__ void pv_blk(const u32x4 (&pf)[4], f32x16& o0, f32x16& o1, LAS const unsigned char* vbase) {
; #pragma unroll
;     for (int ks = 0; ks < 4; ++ks) {
;         const bf16x8 p = __builtin_bit_cast(bf16x8, pf[ks]);
;         { const s16x4 lo = vtr(vbase + ks * 1024), hh = vtr(vbase + ks * 1024 + 512); const bf16x8 vf = {lo[0], lo[1], lo[2], lo[3], hh[0], hh[1], hh[2], hh[3]};
;           o0 = __builtin_amdgcn_mfma_f32_32x32x16_bf16(vf, p, o0, 0, 0, 0); }
;         { const s16x4 lo = vtr(vbase + 4096 + ks * 1024), hh = vtr(vbase + 4096 + ks * 1024 + 512); const bf16x8 vf = {lo[0], lo[1], lo[2], lo[3], hh[0], hh[1], hh[2], hh[3]};
;           o1 = __builtin_amdgcn_mfma_f32_32x32x16_bf16(vf, p, o1, 0, 0, 0); }
;     }
; }
; __device__ __forceinline__ void attn_unit(const bf16_t* Qh, const bf16_t* Kh, const bf16_t* Vh, bf16_t* Oh  , int S, int qb, LAS unsigned char* lds, int tid) {
;     ...
;         ka = GLD(u32x4, Kg + (size_t)tn * 768 + kc0); kb = GLD(u32x4, Kg + (size_t)tn * 768 + kc1); va = GLD(u32x4, Vg + (size_t)tn * 512 + tid);
;         u32x4 pf[4];
;         {
;             f32x16 p0 = {}, p1 = {};
; #pragma unroll
;             for (int s = 0; s < 6; ++s) {
;                 const bf16x8 a0 = *(const LAS bf16x8*)(lds + cur + kfo + s * 32), a1 = *(const LAS bf16x8*)(lds + cur + kfo + 32 * KPITCH + s * 32);
	v_mfma_f32_32x32x16_bf16 v[64:79], v[176:179], v[186:189], v[64:79]
	v_mfma_f32_32x32x16_bf16 v[80:95], v[180:183], v[186:189], v[80:95]
	ds_read_b128 v[176:179], v155 offset:96
	ds_read_b128 v[180:183], v155 offset:6752
	ds_read_b128 v[186:189], v135 offset:46080
	v_add_f32_e32 v141, v141, v106
	v_add_f32_e32 v166, v166, v107
	v_cvt_pk_bf16_f32 v100, v104, v105
	v_cvt_pk_bf16_f32 v101, v106, v107
	v_exp_f32_e64 v112, v112
	v_exp_f32_e32 v113, v113
	v_exp_f32_e32 v114, v114
	v_exp_f32_e32 v115, v115
	v_add_f32_e32 v141, v141, v108
	v_add_f32_e32 v166, v166, v109
	s_waitcnt lgkmcnt(3)
	v_mfma_f32_32x32x16_bf16 v[64:79], v[128:131], v[162:165], v[64:79]
	v_mfma_f32_32x32x16_bf16 v[80:95], v[142:145], v[162:165], v[80:95]
	ds_read_b128 v[128:131], v155 offset:128
	ds_read_b128 v[142:145], v155 offset:6784
	ds_read_b128 v[162:165], v135 offset:47104
	v_add_f32_e32 v141, v141, v110
	v_add_f32_e32 v166, v166, v111
	v_cvt_pk_bf16_f32 v102, v108, v109
	v_cvt_pk_bf16_f32 v103, v110, v111
	v_exp_f32_e32 v116, v116
	v_exp_f32_e32 v117, v117
	v_exp_f32_e32 v118, v118
	v_exp_f32_e32 v119, v119
	v_add_f32_e32 v141, v141, v112
	s_waitcnt lgkmcnt(3)
	v_mfma_f32_32x32x16_bf16 v[64:79], v[176:179], v[186:189], v[64:79]
	v_mfma_f32_32x32x16_bf16 v[80:95], v[180:183], v[186:189], v[80:95]
	ds_read_b128 v[176:179], v155 offset:160
	ds_read_b128 v[180:183], v155 offset:6816
	ds_read_b128 v[186:189], v135 offset:48128
	v_add_f32_e64 v166, v166, v113
	v_add_f32_e32 v141, v141, v114
	v_add_f32_e32 v166, v166, v115
	v_cvt_pk_bf16_f32 v104, v112, v113
	v_cvt_pk_bf16_f32 v105, v114, v115
	v_exp_f32_e32 v120, v120
	v_exp_f32_e32 v121, v121
	v_exp_f32_e32 v122, v122
	v_exp_f32_e32 v123, v123
	v_add_f32_e32 v141, v141, v116
	s_waitcnt lgkmcnt(3)
	v_mfma_f32_32x32x16_bf16 v[64:79], v[128:131], v[162:165], v[64:79]
	v_mfma_f32_32x32x16_bf16 v[80:95], v[142:145], v[162:165], v[80:95]
	ds_read_b64_tr_b16 v[128:129], v158 offset:34816
	ds_read_b64_tr_b16 v[130:131], v158 offset:35328
	ds_read_b64_tr_b16 v[142:143], v158 offset:38912
	ds_read_b64_tr_b16 v[144:145], v158 offset:39424
	v_add_f32_e64 v166, v166, v117
	v_add_f32_e32 v141, v141, v118
	v_add_f32_e32 v166, v166, v119
	v_cvt_pk_bf16_f32 v106, v116, v117
	v_cvt_pk_bf16_f32 v107, v118, v119
	v_exp_f32_e64 v124, v124
	v_exp_f32_e32 v125, v125
	v_exp_f32_e32 v126, v126
	v_exp_f32_e32 v127, v127
	s_waitcnt lgkmcnt(4)
	v_mfma_f32_32x32x16_bf16 v[64:79], v[176:179], v[186:189], v[64:79]
	v_mfma_f32_32x32x16_bf16 v[80:95], v[180:183], v[186:189], v[80:95]
	ds_read_b64_tr_b16 v[176:177], v158 offset:35840
	ds_read_b64_tr_b16 v[178:179], v158 offset:36352
	ds_read_b64_tr_b16 v[180:181], v158 offset:39936
	ds_read_b64_tr_b16 v[182:183], v158 offset:40448
	v_add_f32_e32 v141, v141, v120
	v_add_f32_e32 v166, v166, v121
	v_add_f32_e32 v141, v141, v122
	v_add_f32_e32 v166, v166, v123
	v_cvt_pk_bf16_f32 v108, v120, v121
	v_cvt_pk_bf16_f32 v109, v122, v123
	v_add_f32_e32 v141, v141, v124
	v_add_f32_e32 v166, v166, v125
	v_add_f32_e32 v141, v141, v126
	v_add_f32_e32 v166, v166, v127
	v_cvt_pk_bf16_f32 v110, v124, v125
	v_cvt_pk_bf16_f32 v111, v126, v127
	v_add_f32_e32 v141, v141, v166
	s_waitcnt lgkmcnt(4)
	v_mfma_f32_32x32x16_bf16 v[48:63], v[128:131], v[96:99], v[48:63]
	v_mfma_f32_32x32x16_bf16 v[32:47], v[142:145], v[96:99], v[32:47]
	ds_read_b64_tr_b16 v[128:129], v158 offset:36864
	ds_read_b64_tr_b16 v[130:131], v158 offset:37376
	ds_read_b64_tr_b16 v[142:143], v158 offset:40960
	ds_read_b64_tr_b16 v[144:145], v158 offset:41472
	v_max3_f32 v248, v64, v65, v66
	v_max3_f32 v249, v80, v81, v82
	v_max3_f32 v248, v248, v67, v68
	v_max3_f32 v249, v249, v83, v84
	v_max3_f32 v248, v248, v69, v70
	v_max3_f32 v249, v249, v85, v86
	v_max3_f32 v248, v248, v71, v72
	v_max3_f32 v249, v249, v87, v88
	v_max3_f32 v248, v248, v73, v74
	v_max3_f32 v249, v249, v89, v90
	v_max3_f32 v248, v248, v75, v76
	v_max3_f32 v249, v249, v91, v92
	v_max3_f32 v248, v248, v77, v78
	v_max3_f32 v249, v249, v93, v94
	s_waitcnt lgkmcnt(4)
	s_nop 0
	v_mfma_f32_32x32x16_bf16 v[48:63], v[176:179], v[100:103], v[48:63]
	v_mfma_f32_32x32x16_bf16 v[32:47], v[180:183], v[100:103], v[32:47]
	ds_read_b64_tr_b16 v[176:177], v158 offset:37888
	ds_read_b64_tr_b16 v[178:179], v158 offset:38400
	ds_read_b64_tr_b16 v[180:181], v158 offset:41984
	ds_read_b64_tr_b16 v[182:183], v158 offset:42496
	v_max3_f32 v248, v248, v79, v95
	v_max_f32_e64 v248, v248, v249
	v_mov_b32_e32 v251, v248
	s_nop 1
	v_permlane32_swap_b32_e32 v248, v251
	v_max_f32_e32 v167, v248, v251
	v_cmp_lt_f32_e32 vcc, s72, v167
	s_cbranch_vccnz .Lmla_rescAe
; #define LAS __attribute__((address_space(3)))
; __device__ __forceinline__ void softmax_blk(f32x16& p0, f32x16& p1, f32x16& o0, f32x16& o1, float& mhat, float& lrun, u32x4 (&pf)[4], bool first) {
;     float r0 = max2_(p0[0], p0[1]), r1 = max2_(p1[0], p1[1]);
; #pragma unroll
;     for (int e = 2; e < 16; ++e) { r0 = max2_(r0, p0[e]); r1 = max2_(r1, p1[e]); }
;     const float rm = swap_max(max2_(r0, r1));
;     if (first || __any(rm - mhat > THR)) {
;         const float mn = first ? rm : fmaxf(rm, mhat); const float f = first ? 0.f : __builtin_amdgcn_exp2f(mhat - mn); mhat = mn; lrun *= f;
; #pragma unroll
;         for (int e = 0; e < 16; ++e) { o0[e] *= f; o1[e] *= f; }
;     }
;     float s0 = 0.f, s1 = 0.f;
; #pragma unroll
;     for (int e = 0; e < 16; ++e) { p0[e] = __builtin_amdgcn_exp2f(p0[e] - mhat); p1[e] = __builtin_amdgcn_exp2f(p1[e] - mhat); s0 += p0[e]; s1 += p1[e]; }
;     lrun += s0 + s1;
;     pf[0] = MLA_PACK(p0, 0); pf[1] = MLA_PACK(p0, 8); pf[2] = MLA_PACK(p1, 0); pf[3] = MLA_PACK(p1, 8);
; }
; __device__ __forceinline__ void pv_blk(const u32x4 (&pf)[4], f32x16& o0, f32x16& o1, LAS const unsigned char* vbase) {
; #pragma unroll
;     for (int ks = 0; ks < 4; ++ks) {
;         const bf16x8 p = __builtin_bit_cast(bf16x8, pf[ks]);
;         { const s16x4 lo = vtr(vbase + ks * 1024), hh = vtr(vbase + ks * 1024 + 512); const bf16x8 vf = {lo[0], lo[1], lo[2], lo[3], hh[0], hh[1], hh[2], hh[3]};
;           o0 = __builtin_amdgcn_mfma_f32_32x32x16_bf16(vf, p, o0, 0, 0, 0); }
;         { const s16x4 lo = vtr(vbase + 4096 + ks * 1024), hh = vtr(vbase + 4096 + ks * 1024 + 512); const bf16x8 vf = {lo[0], lo[1], lo[2], lo[3], hh[0], hh[1], hh[2], hh[3]};
;           o1 = __builtin_amdgcn_mfma_f32_32x32x16_bf16(vf, p, o1, 0, 0, 0); }
;     }
; }
; __device__ __forceinline__ void attn_unit(const bf16_t* Qh, const bf16_t* Kh, const bf16_t* Vh, bf16_t* Oh  , int S, int qb, LAS unsigned char* lds, int tid) {
;     ...
;         ka = GLD(u32x4, Kg + (size_t)tn * 768 + kc0); kb = GLD(u32x4, Kg + (size_t)tn * 768 + kc1); va = GLD(u32x4, Vg + (size_t)tn * 512 + tid);
;         u32x4 pf[4];
;         {
;             f32x16 p0 = {}, p1 = {};
; #pragma unroll
;             for (int s = 0; s < 6; ++s) {
;                 const bf16x8 a0 = *(const LAS bf16x8*)(lds + cur + kfo + s * 32), a1 = *(const LAS bf16x8*)(lds + cur + kfo + 32 * KPITCH + s * 32);
.Lmla_rescAe_back:
	v_exp_f32_e32 v64, v64
	v_exp_f32_e32 v65, v65
	v_exp_f32_e32 v66, v66
	s_waitcnt lgkmcnt(4)
	v_mfma_f32_32x32x16_bf16 v[48:63], v[128:131], v[104:107], v[48:63]
	v_mfma_f32_32x32x16_bf16 v[32:47], v[142:145], v[104:107], v[32:47]
	ds_read_b128 v[128:131], v155
	ds_read_b128 v[142:145], v155 offset:6656
	ds_read_b128 v[162:165], v135 offset:49152
	v_exp_f32_e64 v67, v67
	v_exp_f32_e32 v68, v68
	v_exp_f32_e32 v69, v69
	v_exp_f32_e32 v70, v70
	v_exp_f32_e32 v71, v71
	v_add_f32_e32 v166, v64, v65
	v_add_f32_e32 v140, v140, v66
	v_add_f32_e32 v166, v166, v67
	s_waitcnt lgkmcnt(3)
	v_mfma_f32_32x32x16_bf16 v[48:63], v[176:179], v[108:111], v[48:63]
	v_mfma_f32_32x32x16_bf16 v[32:47], v[180:183], v[108:111], v[32:47]
	ds_read_b128 v[176:179], v155 offset:32
	ds_read_b128 v[180:183], v155 offset:6688
	ds_read_b128 v[186:189], v135 offset:50176
	v_cvt_pk_bf16_f32 v64, v64, v65
	v_cvt_pk_bf16_f32 v65, v66, v67
	v_exp_f32_e32 v72, v72
	v_exp_f32_e32 v73, v73
	v_exp_f32_e32 v74, v74
	v_exp_f32_e32 v75, v75
	v_add_f32_e32 v140, v140, v68
	v_add_f32_e32 v166, v166, v69
	v_add_f32_e32 v140, v140, v70
	s_waitcnt lgkmcnt(3)
	v_mfma_f32_32x32x16_bf16 v[96:111], v[128:131], v[162:165], v[190:205]
	v_mfma_f32_32x32x16_bf16 v[112:127], v[142:145], v[162:165], v[190:205]
	ds_read_b128 v[128:131], v155 offset:64
	ds_read_b128 v[142:145], v155 offset:6720
	ds_read_b128 v[162:165], v135 offset:51200
	v_add_f32_e64 v166, v166, v71
	v_cvt_pk_bf16_f32 v66, v68, v69
	v_cvt_pk_bf16_f32 v67, v70, v71
	v_exp_f32_e64 v76, v76
	v_exp_f32_e32 v77, v77
	v_exp_f32_e32 v78, v78
	v_exp_f32_e32 v79, v79
	v_add_f32_e32 v140, v140, v72
	v_add_f32_e32 v166, v166, v73
	s_waitcnt lgkmcnt(3)
	v_mfma_f32_32x32x16_bf16 v[96:111], v[176:179], v[186:189], v[96:111]
	v_mfma_f32_32x32x16_bf16 v[112:127], v[180:183], v[186:189], v[112:127]
	ds_read_b128 v[176:179], v155 offset:96
	ds_read_b128 v[180:183], v155 offset:6752
	ds_read_b128 v[186:189], v135 offset:52224
	v_add_f32_e32 v140, v140, v74
	v_add_f32_e32 v166, v166, v75
	v_cvt_pk_bf16_f32 v68, v72, v73
	v_cvt_pk_bf16_f32 v69, v74, v75
	v_exp_f32_e64 v80, v80
	v_exp_f32_e32 v81, v81
	v_exp_f32_e32 v82, v82
	v_exp_f32_e32 v83, v83
	v_add_f32_e32 v140, v140, v76
	v_add_f32_e32 v166, v166, v77
	s_waitcnt lgkmcnt(3)
	v_mfma_f32_32x32x16_bf16 v[96:111], v[128:131], v[162:165], v[96:111]
	v_mfma_f32_32x32x16_bf16 v[112:127], v[142:145], v[162:165], v[112:127]
	ds_read_b128 v[128:131], v155 offset:128
	ds_read_b128 v[142:145], v155 offset:6784
	ds_read_b128 v[162:165], v135 offset:53248
	v_add_f32_e32 v140, v140, v78
	v_add_f32_e32 v166, v166, v79
	v_cvt_pk_bf16_f32 v70, v76, v77
	v_cvt_pk_bf16_f32 v71, v78, v79
	v_exp_f32_e32 v84, v84
	v_exp_f32_e32 v85, v85
	v_exp_f32_e32 v86, v86
	v_exp_f32_e32 v87, v87
	v_add_f32_e32 v140, v140, v80
	s_waitcnt lgkmcnt(3)
	v_mfma_f32_32x32x16_bf16 v[96:111], v[176:179], v[186:189], v[96:111]
	v_mfma_f32_32x32x16_bf16 v[112:127], v[180:183], v[186:189], v[112:127]
	ds_read_b128 v[176:179], v155 offset:160
	ds_read_b128 v[180:183], v155 offset:6816
	ds_read_b128 v[186:189], v135 offset:54272
	v_add_f32_e64 v166, v166, v81
	v_add_f32_e32 v140, v140, v82
	v_add_f32_e32 v166, v166, v83
	v_cvt_pk_bf16_f32 v72, v80, v81
	v_cvt_pk_bf16_f32 v73, v82, v83
	v_exp_f32_e32 v88, v88
	v_exp_f32_e32 v89, v89
	v_exp_f32_e32 v90, v90
	v_exp_f32_e32 v91, v91
	v_add_f32_e32 v140, v140, v84
	s_waitcnt vmcnt(0)
	ds_write_b128 v150, v[218:221] offset:21504
	ds_write_b128 v159, v[222:225]
	ds_write_b128 v157, v[226:229] offset:13312
	s_waitcnt lgkmcnt(6)
	s_nop 0
	v_mfma_f32_32x32x16_bf16 v[96:111], v[128:131], v[162:165], v[96:111]
	v_mfma_f32_32x32x16_bf16 v[112:127], v[142:145], v[162:165], v[112:127]
	v_add_f32_e64 v166, v166, v85
	v_add_f32_e32 v140, v140, v86
	v_add_f32_e32 v166, v166, v87
	v_cvt_pk_bf16_f32 v74, v84, v85
	v_cvt_pk_bf16_f32 v75, v86, v87
	v_exp_f32_e64 v92, v92
	v_exp_f32_e32 v93, v93
	v_exp_f32_e32 v94, v94
	v_exp_f32_e32 v95, v95
	s_waitcnt lgkmcnt(3)
	v_mfma_f32_32x32x16_bf16 v[96:111], v[176:179], v[186:189], v[96:111]
	v_mfma_f32_32x32x16_bf16 v[112:127], v[180:183], v[186:189], v[112:127]
	v_add_f32_e32 v140, v140, v88
	v_add_f32_e32 v166, v166, v89
	v_add_f32_e32 v140, v140, v90
	v_add_f32_e32 v166, v166, v91
	v_cvt_pk_bf16_f32 v76, v88, v89
	v_cvt_pk_bf16_f32 v77, v90, v91
	v_add_f32_e32 v140, v140, v92
	v_add_f32_e32 v166, v166, v93
	v_add_f32_e32 v140, v140, v94
	v_add_f32_e32 v166, v166, v95
	v_cvt_pk_bf16_f32 v78, v92, v93
	v_cvt_pk_bf16_f32 v79, v94, v95
	v_add_f32_e64 v140, v140, v166
	s_waitcnt lgkmcnt(0)
	s_barrier
	s_add_i32 s1, s1, 1
	s_branch .Lmla_top

; __device__ __forceinline__ void attn_unit(const bf16_t* Qh, const bf16_t* Kh, const bf16_t* Vh, bf16_t* Oh  , int S, int qb, LAS unsigned char* lds, int tid) {
;     ...
;     f32x16 oa0 = {}, oa1 = {}, ob0 = {}, ob1 = {}; float ma = 0.f, la = 0.f, mb = 0.f, lb = 0.f;
;     const unsigned kfo = (unsigned)(r32 * KPITCH + hi * 16);
;     const unsigned vb = (unsigned)(KBYTES + ((lane >> 4) & 1) * 32 + (lane & 3) * 8 + (4 * hi + ((lane & 15) >> 2)) * 64);
.Lalt_entry:
	v_mov_b64_e32 v[0:1], 0
	v_mov_b64_e32 v[2:3], 0
	v_mov_b64_e32 v[4:5], 0
	v_mov_b64_e32 v[6:7], 0
	v_mov_b64_e32 v[8:9], 0
	v_mov_b64_e32 v[10:11], 0
	v_mov_b64_e32 v[12:13], 0
	v_mov_b64_e32 v[14:15], 0
	v_mov_b64_e32 v[16:17], 0
	v_mov_b64_e32 v[18:19], 0
	v_mov_b64_e32 v[20:21], 0
	v_mov_b64_e32 v[22:23], 0
	v_mov_b64_e32 v[24:25], 0
	v_mov_b64_e32 v[26:27], 0
	v_mov_b64_e32 v[28:29], 0
	v_mov_b64_e32 v[30:31], 0
	v_mov_b64_e32 v[32:33], 0
	v_mov_b64_e32 v[34:35], 0
	v_mov_b64_e32 v[36:37], 0
	v_mov_b64_e32 v[38:39], 0
	v_mov_b64_e32 v[40:41], 0
	v_mov_b64_e32 v[42:43], 0
	v_mov_b64_e32 v[44:45], 0
	v_mov_b64_e32 v[46:47], 0
	v_mov_b64_e32 v[48:49], 0
	v_mov_b64_e32 v[50:51], 0
	v_mov_b64_e32 v[52:53], 0
	v_mov_b64_e32 v[54:55], 0
	v_mov_b64_e32 v[56:57], 0
	v_mov_b64_e32 v[58:59], 0
	v_mov_b64_e32 v[60:61], 0
	v_mov_b64_e32 v[62:63], 0
	v_mov_b32_e32 v140, 0
	v_mov_b32_e32 v141, 0
	v_lshlrev_b32_e32 v171, 4, v172
	v_lshlrev_b32_e32 v184, 4, v132
	v_lshlrev_b32_e32 v146, 4, v174
	v_readfirstlane_b32 s100, v138
	v_readfirstlane_b32 s101, v139
	s_add_u32 s26, s16, 0x3000
	s_addc_u32 s27, s17, 0
	s_mov_b32 s1, 1
	v_readfirstlane_b32 s4, v172
	s_nop 3
	s_cmp_ge_u32 s4, 0x100
	s_nop 0
	s_nop 0
